# grid barrier: all blocks poll the top-level generation word directly (per-XCD release word hop removed)
# speedup vs baseline: 1.0116x; 1.0116x over previous
; DEV unsigned xb_ld(unsigned* p)              { return __hip_atomic_load(p, __ATOMIC_RELAXED, __HIP_MEMORY_SCOPE_AGENT); }
; DEV unsigned xb_add(unsigned* p, unsigned v) { return __hip_atomic_fetch_add(p, v, __ATOMIC_RELAXED, __HIP_MEMORY_SCOPE_AGENT); }
; #define XB_SPIN(cond, bar) do { unsigned _sp = 0; while (cond) { __builtin_amdgcn_s_sleep(1); \
;     if ((++_sp & 255u) == 0u) { if (xb_ld(&(bar)[XB_TMO])) break; if (_sp > XB_SPIN_CAP) { atomicAdd(&(bar)[XB_TMO], 1u); break; } } } } while (0)
; DEV void xcd_barrier(const XcdBarrier& b) {
;     ...
;     unsigned nloc = b.st[0], nx = b.st[1];
;     if (nloc == 0u) { xcd_barrier_complete(bar, b.x, nloc, nx); b.st[0] = nloc; b.st[1] = nx; }
;     const unsigned old = xb_add(&bar[XB_XSUB(b.x)], 1u);
;     const unsigned gen = old / nloc;
;     if (old + 1u == (gen + 1u) * nloc) {
;       __builtin_amdgcn_fence(__ATOMIC_RELEASE, "agent");
;       asm volatile("s_waitcnt vmcnt(0)" ::: "memory");
;       const unsigned og = xb_add(&bar[XB_TOP], 1u);
;       const unsigned tg = og / nx;
;       if (og + 1u == (tg + 1u) * nx) xb_add(&bar[XB_TOPGEN], 1u);
;       else XB_SPIN(xb_ld(&bar[XB_TOPGEN]) == tg, bar);
;       __builtin_amdgcn_fence(__ATOMIC_ACQUIRE, "agent");
;       xb_add(&bar[XB_XGEN(b.x)], 1u);
;       asm volatile("s_waitcnt vmcnt(0)" ::: "memory");
;     } else {
;       XB_SPIN(xb_ld(&bar[XB_XGEN(b.x)]) == gen, bar);
.LBB0_29:
	s_or_b64 exec, exec, s[2:3]
	v_cvt_f32_u32_e32 v4, v2
	s_waitcnt vmcnt(0)
	v_readfirstlane_b32 s2, v3
	v_sub_u32_e32 v3, 0, v2
	v_rcp_iflag_f32_e32 v4, v4
	v_add_u32_e32 v5, s2, v1
	v_mul_f32_e32 v4, 0x4f7ffffe, v4
	v_cvt_u32_f32_e32 v4, v4
	v_mul_lo_u32 v1, v3, v4
	v_mul_hi_u32 v1, v4, v1
	v_add_u32_e32 v1, v4, v1
	v_mul_hi_u32 v1, v5, v1
	v_mul_lo_u32 v3, v1, v2
	v_sub_u32_e32 v3, v5, v3
	v_add_u32_e32 v4, 1, v1
	v_sub_u32_e32 v6, v3, v2
	v_cmp_ge_u32_e32 vcc, v3, v2
	s_nop 1
	v_cndmask_b32_e32 v1, v1, v4, vcc
	v_cndmask_b32_e32 v3, v3, v6, vcc
	v_add_u32_e32 v4, 1, v1
	v_cmp_ge_u32_e32 vcc, v3, v2
	v_add_u32_e32 v3, 1, v5
	s_nop 0
	v_cndmask_b32_e32 v1, v1, v4, vcc
	v_mul_lo_u32 v4, v2, v1
	v_add_u32_e32 v2, v4, v2
	v_cmp_ne_u32_e32 vcc, v3, v2
	s_and_saveexec_b64 s[2:3], vcc
	s_xor_b64 s[2:3], exec, s[2:3]
	s_cbranch_execz .LBB0_43
	v_readlane_b32 s4, v249, 31
	v_readlane_b32 s5, v249, 32
	s_waitcnt lgkmcnt(0)
	s_nop 3
	global_load_dword v0, v169, s[4:5] sc1
	s_waitcnt vmcnt(0)
	v_cmp_eq_u32_e32 vcc, v0, v1
	s_and_saveexec_b64 s[4:5], vcc
	s_cbranch_execz .LBB0_42
	s_mov_b32 s6, 1
	s_mov_b64 s[8:9], 0
	s_branch .LBB0_33

; DEV unsigned xb_ld(unsigned* p)              { return __hip_atomic_load(p, __ATOMIC_RELAXED, __HIP_MEMORY_SCOPE_AGENT); }
; #define XB_SPIN(cond, bar) do { unsigned _sp = 0; while (cond) { __builtin_amdgcn_s_sleep(1); \
;     if ((++_sp & 255u) == 0u) { if (xb_ld(&(bar)[XB_TMO])) break; if (_sp > XB_SPIN_CAP) { atomicAdd(&(bar)[XB_TMO], 1u); break; } } } } while (0)
; DEV void xcd_barrier(const XcdBarrier& b) {
;     ...
;       XB_SPIN(xb_ld(&bar[XB_XGEN(b.x)]) == gen, bar);
.LBB0_35:
	v_readlane_b32 s14, v249, 31
	v_readlane_b32 s15, v249, 32
	s_add_i32 s6, s6, 1
	s_mov_b64 s[16:17], -1
	s_nop 2
	global_load_dword v0, v169, s[14:15] sc1
	s_waitcnt vmcnt(0)
	v_cmp_ne_u32_e32 vcc, v0, v1
	s_orn2_b64 s[14:15], vcc, exec
	s_branch .LBB0_32

; DEV unsigned xb_ld(unsigned* p)              { return __hip_atomic_load(p, __ATOMIC_RELAXED, __HIP_MEMORY_SCOPE_AGENT); }
; DEV unsigned xb_add(unsigned* p, unsigned v) { return __hip_atomic_fetch_add(p, v, __ATOMIC_RELAXED, __HIP_MEMORY_SCOPE_AGENT); }
; #define XB_SPIN(cond, bar) do { unsigned _sp = 0; while (cond) { __builtin_amdgcn_s_sleep(1); \
;     if ((++_sp & 255u) == 0u) { if (xb_ld(&(bar)[XB_TMO])) break; if (_sp > XB_SPIN_CAP) { atomicAdd(&(bar)[XB_TMO], 1u); break; } } } } while (0)
; DEV void xcd_barrier(const XcdBarrier& b) {
;     ...
;       else XB_SPIN(xb_ld(&bar[XB_TOPGEN]) == tg, bar);
;       __builtin_amdgcn_fence(__ATOMIC_ACQUIRE, "agent");
;       xb_add(&bar[XB_XGEN(b.x)], 1u);
;       asm volatile("s_waitcnt vmcnt(0)" ::: "memory");
.LBB0_60:
	s_or_b64 exec, exec, s[2:3]
	s_mov_b64 s[2:3], exec
	v_mbcnt_lo_u32_b32 v0, s2, 0
	v_mbcnt_hi_u32_b32 v0, s3, v0
	v_cmp_eq_u32_e32 vcc, 0, v0
	s_waitcnt vmcnt(0)
	buffer_inv sc1
.LBB0_62:
	s_waitcnt vmcnt(0)
.LBB0_63:
	s_or_b64 exec, exec, s[0:1]
	s_mov_b64 s[0:1], 0
	s_waitcnt lgkmcnt(0)
	s_barrier
